# merge phase rewritten as one software-pipelined stream: 24 K-steps per task, global loads 4 K-tiles ahead across branch and task boundaries, per-branch gate accumulation
# speedup vs baseline: 1.0179x; 1.0126x over previous
; template <bool RFA, bool RFB, class LA, class LB, class EPI>
; DI void gemm_tile2s(u16* smem, int nk, LA la, LB lb, EPI epi) {
;   const int tid = tidx(), lane = tid & 63, wave = tid >> 6;
;   const int wm = wave >> 2, wn = wave & 3, lr = lane & 31, lh = lane >> 5;
;   u16* As = smem;
;   u16* Bs = smem + 2 * TILE_ELEMS;
;   f32x16 acc[2];
;   acc[0] = zero16(); acc[1] = zero16();
;   u32x4 ra0[2], rb0[2], ra1[2], rb1[2];
;   auto ld = [&](u32x4 (&ra)[2], u32x4 (&rb)[2], int kt) __attribute__((always_inline)) {
;     const int k0 = kt * 64;
; #pragma unroll
;     for (int i = 0; i < 2; ++i) { const int c = tid + NTH * i; ra[i] = la(A_ROW(c), k0 + A_KC(c) * 8); rb[i] = lb(B_ROW(c), k0 + B_KC(c) * 8); }
;   };
;   auto stl = [&](u32x4 (&ra)[2], u32x4 (&rb)[2], int buf) __attribute__((always_inline)) {
; #pragma unroll
;     for (int i = 0; i < 2; ++i) {
;       const int c = tid + NTH * i;
;       *(u32x4*)(As + buf * TILE_ELEMS + A_ROW(c) * LDT + A_KC(c) * 8) = ra[i];
;       *(u32x4*)(Bs + buf * TILE_ELEMS + B_ROW(c) * LDT + B_KC(c) * 8) = rb[i];
;     }
;   };
;   auto compute = [&](int buf) __attribute__((always_inline)) {
;     const u16* Ab = As + buf * TILE_ELEMS + (wm * 64 + lr) * LDT + lh * 8;
;     const u16* Bb = Bs + buf * TILE_ELEMS + (wn * 32 + lr) * LDT + lh * 8;
; #pragma unroll
;     for (int ks = 0; ks < 4; ++ks) {
;       const bf16x8 a0 = *(const bf16x8*)(Ab + ks * 16);
;       const bf16x8 a1 = *(const bf16x8*)(Ab + 32 * LDT + ks * 16);
;       const bf16x8 b = *(const bf16x8*)(Bb + ks * 16);
;       acc[0] = mfma(a0, b, acc[0]);
;       acc[1] = mfma(a1, b, acc[1]);
;     }
;   };
;   ld(ra0, rb0, 0);
;   if (nk > 1) ld(ra1, rb1, 1);
;   stl(ra0, rb0, 0);
;   if (nk > 2) ld(ra0, rb0, 2);
;   __syncthreads();
; #pragma unroll 1
;   for (int kt = 0; kt < nk; kt += 2) {
;     compute(0);
; DI void phase_merge(const Prm& p, u16* smem, int l, int& base) {
;   TASK_LOOP(t, 8 * 128, base) {
;     const int tn = t & 7, tm = t >> 3, n0 = tn * 128, m0 = tm * 128;
;     f32x16 macc[2];
;     macc[0] = zero16(); macc[1] = zero16();
;     merge_branch(p, smem, p.PaT + (size_t)l * 1024 * 768, p.UT, 768, 0, n0, m0, macc);
;     merge_branch(p, smem, p.PbT + (size_t)l * 1024 * 128, p.ob, 128, 1, n0, m0, macc);
;     ...
;     merge_branch(p, smem, p.PdT + (size_t)l * 1024 * 256, p.od, 256, 3, n0, m0, macc);
.LBB0_2250:
	v_readlane_b32 s36, v253, 28
	v_readlane_b32 s37, v253, 29
	v_readlane_b32 s38, v253, 30
	v_readlane_b32 s39, v253, 31
	v_readlane_b32 s40, v252, 4
	v_readlane_b32 s41, v252, 5
	v_readlane_b32 s42, v252, 6
	v_readlane_b32 s43, v252, 7
	v_readlane_b32 s48, v253, 20
	v_readlane_b32 s49, v253, 21
	v_and_b32_e32 v226, 7, v224
	v_lshlrev_b32_e32 v226, 4, v226
	v_lshrrev_b32_e32 v227, 3, v224
	v_and_b32_e32 v228, 0xffffffe3, v227
	v_lshrrev_b32_e32 v229, 1, v227
	v_and_b32_e32 v229, 12, v229
	v_or_b32_e32 v228, v228, v229
	v_lshlrev_b32_e32 v229, 2, v227
	v_and_b32_e32 v229, 16, v229
	v_or_b32_e32 v228, v228, v229
	s_movk_i32 s52, 0x600
	v_mad_u32_u24 v210, v228, s52, v226
	v_mad_u32_u24 v214, v227, s52, v226
	s_movk_i32 s52, 0x100
	v_mad_u32_u24 v211, v228, s52, v226
	v_mad_u32_u24 v215, v227, s52, v226
	s_movk_i32 s52, 0x300
	v_mad_u32_u24 v212, v228, s52, v226
	v_mad_u32_u24 v216, v227, s52, v226
	s_movk_i32 s52, 0x200
	v_mad_u32_u24 v213, v228, s52, v226
	v_mad_u32_u24 v217, v227, s52, v226
	s_movk_i32 s52, 0x90
	v_mad_u32_u24 v218, v227, s52, v226
	v_lshrrev_b32_e32 v226, 1, v224
	v_and_b32_e32 v227, 16, v226
	v_and_b32_e32 v228, 31, v224
	v_lshrrev_b32_e32 v229, 2, v224
	v_and_b32_e32 v229, 64, v229
	v_and_b32_e32 v226, 0x60, v226
	v_or_b32_e32 v226, v226, v228
	v_or_b32_e32 v228, v229, v228
	v_mad_u32_u24 v219, v228, s52, v227
	v_mad_u32_u24 v220, v226, s52, v227
	v_or_b32_e32 v229, v229, v227
	v_lshlrev_b32_e32 v229, 1, v229
	v_lshl_add_u32 v221, v226, 13, v229
	v_lshl_add_u32 v222, v226, 11, v229
	s_and_b32 s58, s31, 7
	s_lshl_b32 s58, s58, 7
	s_lshr_b32 s59, s31, 3
	s_lshl_b32 s59, s59, 7
	s_mul_i32 s52, s58, 0x600
	s_add_u32 s0, s16, s52
	s_addc_u32 s1, s17, 0
	s_add_u32 s2, s0, 0x18000
	s_addc_u32 s3, s1, 0
	s_mul_i32 s52, s59, 0x600
	s_add_u32 s4, s14, s52
	s_addc_u32 s5, s15, 0
	s_add_u32 s6, s4, 0x18000
	s_addc_u32 s7, s5, 0
	global_load_dwordx4 v[66:69], v210, s[0:1]
	global_load_dwordx4 v[70:73], v210, s[2:3]
	global_load_dwordx4 v[74:77], v214, s[4:5]
	global_load_dwordx4 v[78:81], v214, s[6:7]
	global_load_dwordx4 v[82:85], v210, s[0:1] offset:128
	global_load_dwordx4 v[86:89], v210, s[2:3] offset:128
	global_load_dwordx4 v[90:93], v214, s[4:5] offset:128
	global_load_dwordx4 v[94:97], v214, s[6:7] offset:128
	global_load_dwordx4 v[98:101], v210, s[0:1] offset:256
	global_load_dwordx4 v[102:105], v210, s[2:3] offset:256
	global_load_dwordx4 v[106:109], v214, s[4:5] offset:256
	global_load_dwordx4 v[110:113], v214, s[6:7] offset:256
	global_load_dwordx4 v[114:117], v210, s[0:1] offset:384
	global_load_dwordx4 v[118:121], v210, s[2:3] offset:384
	global_load_dwordx4 v[122:125], v214, s[4:5] offset:384
	global_load_dwordx4 v[126:129], v214, s[6:7] offset:384
	s_waitcnt vmcnt(12)
	ds_write_b128 v218, v[66:69]
	ds_write_b128 v218, v[70:73] offset:9216
	ds_write_b128 v218, v[74:77] offset:36864
	ds_write_b128 v218, v[78:81] offset:46080
	global_load_dwordx4 v[66:69], v210, s[0:1] offset:512
	global_load_dwordx4 v[70:73], v210, s[2:3] offset:512
	global_load_dwordx4 v[74:77], v214, s[4:5] offset:512
	global_load_dwordx4 v[78:81], v214, s[6:7] offset:512
	s_waitcnt vmcnt(0)
	s_waitcnt lgkmcnt(0)
	s_barrier
.Lmrg_task:
	s_lshl_b32 s52, s59, 13
	s_lshl_b32 s53, s58, 1
	s_add_u32 s52, s52, s53
	s_add_u32 s8, s42, s52
	s_addc_u32 s9, s43, 0
	s_add_u32 s10, s8, 0x1000
	s_addc_u32 s11, s9, 0
	s_lshl_b32 s52, s59, 11
	s_add_u32 s52, s52, s53
	s_add_u32 s12, s48, s52
	s_addc_u32 s13, s49, 0
	ds_read_b128 v[130:133], v219
	ds_read_b128 v[134:137], v220 offset:36864
	ds_read_b128 v[138:141], v219 offset:4608
	ds_read_b128 v[142:145], v219 offset:32
	ds_read_b128 v[146:149], v220 offset:36896
	ds_read_b128 v[150:153], v219 offset:4640
	ds_read_b128 v[154:157], v219 offset:64
	ds_read_b128 v[158:161], v220 offset:36928
	ds_read_b128 v[162:165], v219 offset:4672
	ds_read_b128 v[166:169], v219 offset:96
	ds_read_b128 v[170:173], v220 offset:36960
	ds_read_b128 v[174:177], v219 offset:4704
	s_waitcnt lgkmcnt(10)
	v_mfma_f32_32x32x16_bf16 v[18:33], v[130:133], v[134:137], 0
	s_waitcnt lgkmcnt(9)
	v_mfma_f32_32x32x16_bf16 v[2:17], v[138:141], v[134:137], 0
	s_waitcnt lgkmcnt(7)
	v_mfma_f32_32x32x16_bf16 v[18:33], v[142:145], v[146:149], v[18:33]
	s_waitcnt lgkmcnt(6)
	v_mfma_f32_32x32x16_bf16 v[2:17], v[150:153], v[146:149], v[2:17]
	s_waitcnt lgkmcnt(4)
	v_mfma_f32_32x32x16_bf16 v[18:33], v[154:157], v[158:161], v[18:33]
	s_waitcnt lgkmcnt(3)
	v_mfma_f32_32x32x16_bf16 v[2:17], v[162:165], v[158:161], v[2:17]
	s_waitcnt lgkmcnt(1)
	v_mfma_f32_32x32x16_bf16 v[18:33], v[166:169], v[170:173], v[18:33]
	s_waitcnt lgkmcnt(0)
	v_mfma_f32_32x32x16_bf16 v[2:17], v[174:177], v[170:173], v[2:17]
	s_waitcnt vmcnt(16)
	ds_write_b128 v218, v[82:85] offset:18432
	ds_write_b128 v218, v[86:89] offset:27648
	ds_write_b128 v218, v[90:93] offset:55296
	ds_write_b128 v218, v[94:97] offset:64512
	global_load_dwordx4 v[82:85], v210, s[0:1] offset:640
	global_load_dwordx4 v[86:89], v210, s[2:3] offset:640
	global_load_dwordx4 v[90:93], v214, s[4:5] offset:640
	global_load_dwordx4 v[94:97], v214, s[6:7] offset:640
	s_waitcnt lgkmcnt(0)
	s_barrier
; template <bool RFA, bool RFB, class LA, class LB, class EPI>
; DI void gemm_tile2s(u16* smem, int nk, LA la, LB lb, EPI epi) {
;     ...
;   for (int kt = 0; kt < nk; kt += 2) {
;     compute(0);
;     if (kt + 1 < nk) { stl(ra1, rb1, 1); if (kt + 3 < nk) ld(ra1, rb1, kt + 3); }
;     __syncthreads();
;     if (kt + 1 < nk) {
;       compute(1);
;       if (kt + 2 < nk) { stl(ra0, rb0, 0); if (kt + 4 < nk) ld(ra0, rb0, kt + 4); }
;       __syncthreads();
	ds_read_b128 v[130:133], v219 offset:18432
	ds_read_b128 v[134:137], v220 offset:55296
	ds_read_b128 v[138:141], v219 offset:23040
	ds_read_b128 v[142:145], v219 offset:18464
	ds_read_b128 v[146:149], v220 offset:55328
	ds_read_b128 v[150:153], v219 offset:23072
	ds_read_b128 v[154:157], v219 offset:18496
	ds_read_b128 v[158:161], v220 offset:55360
	ds_read_b128 v[162:165], v219 offset:23104
	ds_read_b128 v[166:169], v219 offset:18528
	ds_read_b128 v[170:173], v220 offset:55392
	ds_read_b128 v[174:177], v219 offset:23136
	s_waitcnt lgkmcnt(10)
	v_mfma_f32_32x32x16_bf16 v[18:33], v[130:133], v[134:137], v[18:33]
	s_waitcnt lgkmcnt(9)
	v_mfma_f32_32x32x16_bf16 v[2:17], v[138:141], v[134:137], v[2:17]
	s_waitcnt lgkmcnt(7)
	v_mfma_f32_32x32x16_bf16 v[18:33], v[142:145], v[146:149], v[18:33]
	s_waitcnt lgkmcnt(6)
	v_mfma_f32_32x32x16_bf16 v[2:17], v[150:153], v[146:149], v[2:17]
	s_waitcnt lgkmcnt(4)
	v_mfma_f32_32x32x16_bf16 v[18:33], v[154:157], v[158:161], v[18:33]
	s_waitcnt lgkmcnt(3)
	v_mfma_f32_32x32x16_bf16 v[2:17], v[162:165], v[158:161], v[2:17]
	s_waitcnt lgkmcnt(1)
	v_mfma_f32_32x32x16_bf16 v[18:33], v[166:169], v[170:173], v[18:33]
	s_waitcnt lgkmcnt(0)
	v_mfma_f32_32x32x16_bf16 v[2:17], v[174:177], v[170:173], v[2:17]
	s_waitcnt vmcnt(16)
	ds_write_b128 v218, v[98:101]
	ds_write_b128 v218, v[102:105] offset:9216
	ds_write_b128 v218, v[106:109] offset:36864
	ds_write_b128 v218, v[110:113] offset:46080
	global_load_dwordx4 v[98:101], v210, s[0:1] offset:768
	global_load_dwordx4 v[102:105], v210, s[2:3] offset:768
	global_load_dwordx4 v[106:109], v214, s[4:5] offset:768
	global_load_dwordx4 v[110:113], v214, s[6:7] offset:768
	s_waitcnt lgkmcnt(0)
	s_barrier
	ds_read_b128 v[130:133], v219
	ds_read_b128 v[134:137], v220 offset:36864
	ds_read_b128 v[138:141], v219 offset:4608
	ds_read_b128 v[142:145], v219 offset:32
	ds_read_b128 v[146:149], v220 offset:36896
	ds_read_b128 v[150:153], v219 offset:4640
	ds_read_b128 v[154:157], v219 offset:64
	ds_read_b128 v[158:161], v220 offset:36928
	ds_read_b128 v[162:165], v219 offset:4672
	ds_read_b128 v[166:169], v219 offset:96
	ds_read_b128 v[170:173], v220 offset:36960
	ds_read_b128 v[174:177], v219 offset:4704
	s_waitcnt lgkmcnt(10)
	v_mfma_f32_32x32x16_bf16 v[18:33], v[130:133], v[134:137], v[18:33]
	s_waitcnt lgkmcnt(9)
	v_mfma_f32_32x32x16_bf16 v[2:17], v[138:141], v[134:137], v[2:17]
	s_waitcnt lgkmcnt(7)
	v_mfma_f32_32x32x16_bf16 v[18:33], v[142:145], v[146:149], v[18:33]
	s_waitcnt lgkmcnt(6)
	v_mfma_f32_32x32x16_bf16 v[2:17], v[150:153], v[146:149], v[2:17]
	s_waitcnt lgkmcnt(4)
	v_mfma_f32_32x32x16_bf16 v[18:33], v[154:157], v[158:161], v[18:33]
	s_waitcnt lgkmcnt(3)
	v_mfma_f32_32x32x16_bf16 v[2:17], v[162:165], v[158:161], v[2:17]
	s_waitcnt lgkmcnt(1)
	v_mfma_f32_32x32x16_bf16 v[18:33], v[166:169], v[170:173], v[18:33]
	s_waitcnt lgkmcnt(0)
	v_mfma_f32_32x32x16_bf16 v[2:17], v[174:177], v[170:173], v[2:17]
	s_waitcnt vmcnt(16)
	ds_write_b128 v218, v[114:117] offset:18432
	ds_write_b128 v218, v[118:121] offset:27648
	ds_write_b128 v218, v[122:125] offset:55296
	ds_write_b128 v218, v[126:129] offset:64512
	global_load_dwordx4 v[114:117], v210, s[0:1] offset:896
	global_load_dwordx4 v[118:121], v210, s[2:3] offset:896
	global_load_dwordx4 v[122:125], v214, s[4:5] offset:896
	global_load_dwordx4 v[126:129], v214, s[6:7] offset:896
	s_waitcnt lgkmcnt(0)
	s_barrier
	ds_read_b128 v[130:133], v219 offset:18432
	ds_read_b128 v[134:137], v220 offset:55296
	ds_read_b128 v[138:141], v219 offset:23040
	ds_read_b128 v[142:145], v219 offset:18464
	ds_read_b128 v[146:149], v220 offset:55328
	ds_read_b128 v[150:153], v219 offset:23072
	ds_read_b128 v[154:157], v219 offset:18496
	ds_read_b128 v[158:161], v220 offset:55360
	ds_read_b128 v[162:165], v219 offset:23104
	ds_read_b128 v[166:169], v219 offset:18528
	ds_read_b128 v[170:173], v220 offset:55392
	ds_read_b128 v[174:177], v219 offset:23136
	s_waitcnt lgkmcnt(10)
	v_mfma_f32_32x32x16_bf16 v[18:33], v[130:133], v[134:137], v[18:33]
	s_waitcnt lgkmcnt(9)
	v_mfma_f32_32x32x16_bf16 v[2:17], v[138:141], v[134:137], v[2:17]
	s_waitcnt lgkmcnt(7)
	v_mfma_f32_32x32x16_bf16 v[18:33], v[142:145], v[146:149], v[18:33]
	s_waitcnt lgkmcnt(6)
	v_mfma_f32_32x32x16_bf16 v[2:17], v[150:153], v[146:149], v[2:17]
	s_waitcnt lgkmcnt(4)
	v_mfma_f32_32x32x16_bf16 v[18:33], v[154:157], v[158:161], v[18:33]
	s_waitcnt lgkmcnt(3)
	v_mfma_f32_32x32x16_bf16 v[2:17], v[162:165], v[158:161], v[2:17]
	s_waitcnt lgkmcnt(1)
	v_mfma_f32_32x32x16_bf16 v[18:33], v[166:169], v[170:173], v[18:33]
	s_waitcnt lgkmcnt(0)
	v_mfma_f32_32x32x16_bf16 v[2:17], v[174:177], v[170:173], v[2:17]
	s_waitcnt vmcnt(12)
	ds_write_b128 v218, v[66:69]
	ds_write_b128 v218, v[70:73] offset:9216
	ds_write_b128 v218, v[74:77] offset:36864
	ds_write_b128 v218, v[78:81] offset:46080
	global_load_dwordx4 v[66:69], v210, s[0:1] offset:1024
	global_load_dwordx4 v[70:73], v210, s[2:3] offset:1024
	global_load_dwordx4 v[74:77], v214, s[4:5] offset:1024
	global_load_dwordx4 v[78:81], v214, s[6:7] offset:1024
	s_waitcnt lgkmcnt(0)
	s_barrier
; template <bool RFA, bool RFB, class LA, class LB, class EPI>
; DI void gemm_tile2s(u16* smem, int nk, LA la, LB lb, EPI epi) {
;     ...
;   for (int kt = 0; kt < nk; kt += 2) {
;     compute(0);
;     if (kt + 1 < nk) { stl(ra1, rb1, 1); if (kt + 3 < nk) ld(ra1, rb1, kt + 3); }
;     __syncthreads();
;     if (kt + 1 < nk) {
;       compute(1);
;       if (kt + 2 < nk) { stl(ra0, rb0, 0); if (kt + 4 < nk) ld(ra0, rb0, kt + 4); }
;       __syncthreads();
; template <class ACC>
; DI void merge_branch(const Prm& p, u16* smem, const u16* W, const u16* X, int ld, int bi, int n0, int m0, ACC& macc) {
;     ...
;   auto epi = [&](f32x16 (&acc)[2], int wm, int wn, int lane) __attribute__((always_inline)) {
;     const int lr = lane & 31, lh = lane >> 5;
;     const int tok = m0 + wn * 32 + lr;
; #pragma unroll
;     for (int i = 0; i < 2; ++i)
; #pragma unroll
;       for (int h2 = 0; h2 < 2; ++h2) {
;         const int n = n0 + wm * 64 + i * 32 + 16 * lh + 8 * h2;
;         const u32x4 gz = *(const u32x4*)(p.zg + (size_t)tok * 4096 + bi * 1024 + n);
	ds_read_b128 v[130:133], v219
	ds_read_b128 v[134:137], v220 offset:36864
	ds_read_b128 v[138:141], v219 offset:4608
	ds_read_b128 v[142:145], v219 offset:32
	ds_read_b128 v[146:149], v220 offset:36896
	ds_read_b128 v[150:153], v219 offset:4640
	ds_read_b128 v[154:157], v219 offset:64
	ds_read_b128 v[158:161], v220 offset:36928
	ds_read_b128 v[162:165], v219 offset:4672
	ds_read_b128 v[166:169], v219 offset:96
	ds_read_b128 v[170:173], v220 offset:36960
	ds_read_b128 v[174:177], v219 offset:4704
	s_waitcnt lgkmcnt(10)
	v_mfma_f32_32x32x16_bf16 v[18:33], v[130:133], v[134:137], v[18:33]
	s_waitcnt lgkmcnt(9)
	v_mfma_f32_32x32x16_bf16 v[2:17], v[138:141], v[134:137], v[2:17]
	s_waitcnt lgkmcnt(7)
	v_mfma_f32_32x32x16_bf16 v[18:33], v[142:145], v[146:149], v[18:33]
	s_waitcnt lgkmcnt(6)
	v_mfma_f32_32x32x16_bf16 v[2:17], v[150:153], v[146:149], v[2:17]
	s_waitcnt lgkmcnt(4)
	v_mfma_f32_32x32x16_bf16 v[18:33], v[154:157], v[158:161], v[18:33]
	s_waitcnt lgkmcnt(3)
	v_mfma_f32_32x32x16_bf16 v[2:17], v[162:165], v[158:161], v[2:17]
	s_waitcnt lgkmcnt(1)
	v_mfma_f32_32x32x16_bf16 v[18:33], v[166:169], v[170:173], v[18:33]
	s_waitcnt lgkmcnt(0)
	v_mfma_f32_32x32x16_bf16 v[2:17], v[174:177], v[170:173], v[2:17]
	s_waitcnt vmcnt(12)
	ds_write_b128 v218, v[82:85] offset:18432
	ds_write_b128 v218, v[86:89] offset:27648
	ds_write_b128 v218, v[90:93] offset:55296
	ds_write_b128 v218, v[94:97] offset:64512
	global_load_dwordx4 v[82:85], v210, s[0:1] offset:1152
	global_load_dwordx4 v[86:89], v210, s[2:3] offset:1152
	global_load_dwordx4 v[90:93], v214, s[4:5] offset:1152
	global_load_dwordx4 v[94:97], v214, s[6:7] offset:1152
	s_waitcnt lgkmcnt(0)
	s_barrier
	ds_read_b128 v[130:133], v219 offset:18432
	ds_read_b128 v[134:137], v220 offset:55296
	ds_read_b128 v[138:141], v219 offset:23040
	ds_read_b128 v[142:145], v219 offset:18464
	ds_read_b128 v[146:149], v220 offset:55328
	ds_read_b128 v[150:153], v219 offset:23072
	ds_read_b128 v[154:157], v219 offset:18496
	ds_read_b128 v[158:161], v220 offset:55360
	ds_read_b128 v[162:165], v219 offset:23104
	ds_read_b128 v[166:169], v219 offset:18528
	ds_read_b128 v[170:173], v220 offset:55392
	ds_read_b128 v[174:177], v219 offset:23136
	s_waitcnt lgkmcnt(10)
	v_mfma_f32_32x32x16_bf16 v[18:33], v[130:133], v[134:137], v[18:33]
	s_waitcnt lgkmcnt(9)
	v_mfma_f32_32x32x16_bf16 v[2:17], v[138:141], v[134:137], v[2:17]
	s_waitcnt lgkmcnt(7)
	v_mfma_f32_32x32x16_bf16 v[18:33], v[142:145], v[146:149], v[18:33]
	s_waitcnt lgkmcnt(6)
	v_mfma_f32_32x32x16_bf16 v[2:17], v[150:153], v[146:149], v[2:17]
	s_waitcnt lgkmcnt(4)
	v_mfma_f32_32x32x16_bf16 v[18:33], v[154:157], v[158:161], v[18:33]
	s_waitcnt lgkmcnt(3)
	v_mfma_f32_32x32x16_bf16 v[2:17], v[162:165], v[158:161], v[2:17]
	s_waitcnt lgkmcnt(1)
	v_mfma_f32_32x32x16_bf16 v[18:33], v[166:169], v[170:173], v[18:33]
	s_waitcnt lgkmcnt(0)
	v_mfma_f32_32x32x16_bf16 v[2:17], v[174:177], v[170:173], v[2:17]
	s_waitcnt vmcnt(12)
	ds_write_b128 v218, v[98:101]
	ds_write_b128 v218, v[102:105] offset:9216
	ds_write_b128 v218, v[106:109] offset:36864
	ds_write_b128 v218, v[110:113] offset:46080
	global_load_dwordx4 v[98:101], v210, s[0:1] offset:1280
	global_load_dwordx4 v[102:105], v210, s[2:3] offset:1280
	global_load_dwordx4 v[106:109], v214, s[4:5] offset:1280
	global_load_dwordx4 v[110:113], v214, s[6:7] offset:1280
	global_load_dwordx4 v[178:181], v221, s[8:9]
	global_load_dwordx4 v[182:185], v221, s[8:9] offset:16
	global_load_dwordx4 v[186:189], v221, s[8:9] offset:64
	global_load_dwordx4 v[190:193], v221, s[8:9] offset:80
	s_waitcnt lgkmcnt(0)
	s_barrier
	ds_read_b128 v[130:133], v219
	ds_read_b128 v[134:137], v220 offset:36864
	ds_read_b128 v[138:141], v219 offset:4608
	ds_read_b128 v[142:145], v219 offset:32
	ds_read_b128 v[146:149], v220 offset:36896
	ds_read_b128 v[150:153], v219 offset:4640
	ds_read_b128 v[154:157], v219 offset:64
	ds_read_b128 v[158:161], v220 offset:36928
	ds_read_b128 v[162:165], v219 offset:4672
	ds_read_b128 v[166:169], v219 offset:96
	ds_read_b128 v[170:173], v220 offset:36960
	ds_read_b128 v[174:177], v219 offset:4704
	s_waitcnt lgkmcnt(10)
	v_mfma_f32_32x32x16_bf16 v[18:33], v[130:133], v[134:137], v[18:33]
	s_waitcnt lgkmcnt(9)
	v_mfma_f32_32x32x16_bf16 v[2:17], v[138:141], v[134:137], v[2:17]
	s_waitcnt lgkmcnt(7)
	v_mfma_f32_32x32x16_bf16 v[18:33], v[142:145], v[146:149], v[18:33]
	s_waitcnt lgkmcnt(6)
	v_mfma_f32_32x32x16_bf16 v[2:17], v[150:153], v[146:149], v[2:17]
	s_waitcnt lgkmcnt(4)
	v_mfma_f32_32x32x16_bf16 v[18:33], v[154:157], v[158:161], v[18:33]
	s_waitcnt lgkmcnt(3)
	v_mfma_f32_32x32x16_bf16 v[2:17], v[162:165], v[158:161], v[2:17]
	s_waitcnt lgkmcnt(1)
	v_mfma_f32_32x32x16_bf16 v[18:33], v[166:169], v[170:173], v[18:33]
	s_waitcnt lgkmcnt(0)
	v_mfma_f32_32x32x16_bf16 v[2:17], v[174:177], v[170:173], v[2:17]
	s_waitcnt vmcnt(16)
	ds_write_b128 v218, v[114:117] offset:18432
	ds_write_b128 v218, v[118:121] offset:27648
	ds_write_b128 v218, v[122:125] offset:55296
	ds_write_b128 v218, v[126:129] offset:64512
	global_load_dwordx4 v[114:117], v210, s[0:1] offset:1408
	global_load_dwordx4 v[118:121], v210, s[2:3] offset:1408
	global_load_dwordx4 v[122:125], v214, s[4:5] offset:1408
	global_load_dwordx4 v[126:129], v214, s[6:7] offset:1408
	s_waitcnt lgkmcnt(0)
	s_barrier
; template <bool RFA, bool RFB, class LA, class LB, class EPI>
; DI void gemm_tile2s(u16* smem, int nk, LA la, LB lb, EPI epi) {
;     ...
;   for (int kt = 0; kt < nk; kt += 2) {
;     compute(0);
;     if (kt + 1 < nk) { stl(ra1, rb1, 1); if (kt + 3 < nk) ld(ra1, rb1, kt + 3); }
;     __syncthreads();
;     if (kt + 1 < nk) {
;       compute(1);
;       if (kt + 2 < nk) { stl(ra0, rb0, 0); if (kt + 4 < nk) ld(ra0, rb0, kt + 4); }
;       __syncthreads();
; DI void phase_merge(const Prm& p, u16* smem, int l, int& base) {
;     ...
;     merge_branch(p, smem, p.PaT + (size_t)l * 1024 * 768, p.UT, 768, 0, n0, m0, macc);
;     merge_branch(p, smem, p.PbT + (size_t)l * 1024 * 128, p.ob, 128, 1, n0, m0, macc);
	ds_read_b128 v[130:133], v219 offset:18432
	ds_read_b128 v[134:137], v220 offset:55296
	ds_read_b128 v[138:141], v219 offset:23040
	ds_read_b128 v[142:145], v219 offset:18464
	ds_read_b128 v[146:149], v220 offset:55328
	ds_read_b128 v[150:153], v219 offset:23072
	ds_read_b128 v[154:157], v219 offset:18496
	ds_read_b128 v[158:161], v220 offset:55360
	ds_read_b128 v[162:165], v219 offset:23104
	ds_read_b128 v[166:169], v219 offset:18528
	ds_read_b128 v[170:173], v220 offset:55392
	ds_read_b128 v[174:177], v219 offset:23136
	s_waitcnt lgkmcnt(10)
	v_mfma_f32_32x32x16_bf16 v[18:33], v[130:133], v[134:137], v[18:33]
	s_waitcnt lgkmcnt(9)
	v_mfma_f32_32x32x16_bf16 v[2:17], v[138:141], v[134:137], v[2:17]
	s_waitcnt lgkmcnt(7)
	v_mfma_f32_32x32x16_bf16 v[18:33], v[142:145], v[146:149], v[18:33]
	s_waitcnt lgkmcnt(6)
	v_mfma_f32_32x32x16_bf16 v[2:17], v[150:153], v[146:149], v[2:17]
	s_waitcnt lgkmcnt(4)
	v_mfma_f32_32x32x16_bf16 v[18:33], v[154:157], v[158:161], v[18:33]
	s_waitcnt lgkmcnt(3)
	v_mfma_f32_32x32x16_bf16 v[2:17], v[162:165], v[158:161], v[2:17]
	s_waitcnt lgkmcnt(1)
	v_mfma_f32_32x32x16_bf16 v[18:33], v[166:169], v[170:173], v[18:33]
	s_waitcnt lgkmcnt(0)
	v_mfma_f32_32x32x16_bf16 v[2:17], v[174:177], v[170:173], v[2:17]
	s_waitcnt vmcnt(16)
	ds_write_b128 v218, v[66:69]
	ds_write_b128 v218, v[70:73] offset:9216
	ds_write_b128 v218, v[74:77] offset:36864
	ds_write_b128 v218, v[78:81] offset:46080
	s_mul_i32 s52, s58, 0x100
	s_add_u32 s0, s20, s52
	s_addc_u32 s1, s21, 0
	s_add_u32 s2, s0, 0x4000
	s_addc_u32 s3, s1, 0
	s_mul_i32 s52, s59, 0x100
	s_add_u32 s4, s36, s52
	s_addc_u32 s5, s37, 0
	s_add_u32 s6, s4, 0x4000
	s_addc_u32 s7, s5, 0
	global_load_dwordx4 v[66:69], v211, s[0:1]
	global_load_dwordx4 v[70:73], v211, s[2:3]
	global_load_dwordx4 v[74:77], v215, s[4:5]
	global_load_dwordx4 v[78:81], v215, s[6:7]
	global_load_dwordx4 v[194:197], v221, s[8:9] offset:2048
	global_load_dwordx4 v[198:201], v221, s[8:9] offset:2064
	global_load_dwordx4 v[202:205], v221, s[8:9] offset:2112
	global_load_dwordx4 v[206:209], v221, s[8:9] offset:2128
	s_waitcnt lgkmcnt(0)
	s_barrier
	ds_read_b128 v[130:133], v219
	ds_read_b128 v[134:137], v220 offset:36864
	ds_read_b128 v[138:141], v219 offset:4608
	ds_read_b128 v[142:145], v219 offset:32
	ds_read_b128 v[146:149], v220 offset:36896
	ds_read_b128 v[150:153], v219 offset:4640
	ds_read_b128 v[154:157], v219 offset:64
	ds_read_b128 v[158:161], v220 offset:36928
	ds_read_b128 v[162:165], v219 offset:4672
	ds_read_b128 v[166:169], v219 offset:96
	ds_read_b128 v[170:173], v220 offset:36960
	ds_read_b128 v[174:177], v219 offset:4704
	s_waitcnt lgkmcnt(10)
	v_mfma_f32_32x32x16_bf16 v[18:33], v[130:133], v[134:137], v[18:33]
	s_waitcnt lgkmcnt(9)
	v_mfma_f32_32x32x16_bf16 v[2:17], v[138:141], v[134:137], v[2:17]
	s_waitcnt lgkmcnt(7)
	v_mfma_f32_32x32x16_bf16 v[18:33], v[142:145], v[146:149], v[18:33]
	s_waitcnt lgkmcnt(6)
	v_mfma_f32_32x32x16_bf16 v[2:17], v[150:153], v[146:149], v[2:17]
	s_waitcnt lgkmcnt(4)
	v_mfma_f32_32x32x16_bf16 v[18:33], v[154:157], v[158:161], v[18:33]
	s_waitcnt lgkmcnt(3)
	v_mfma_f32_32x32x16_bf16 v[2:17], v[162:165], v[158:161], v[2:17]
	s_waitcnt lgkmcnt(1)
	v_mfma_f32_32x32x16_bf16 v[18:33], v[166:169], v[170:173], v[18:33]
	s_waitcnt lgkmcnt(0)
	v_mfma_f32_32x32x16_bf16 v[2:17], v[174:177], v[170:173], v[2:17]
	s_waitcnt vmcnt(20)
	ds_write_b128 v218, v[82:85] offset:18432
	ds_write_b128 v218, v[86:89] offset:27648
	ds_write_b128 v218, v[90:93] offset:55296
	ds_write_b128 v218, v[94:97] offset:64512
	global_load_dwordx4 v[82:85], v211, s[0:1] offset:128
	global_load_dwordx4 v[86:89], v211, s[2:3] offset:128
	global_load_dwordx4 v[90:93], v215, s[4:5] offset:128
	global_load_dwordx4 v[94:97], v215, s[6:7] offset:128
	s_waitcnt lgkmcnt(0)
	s_barrier
	ds_read_b128 v[130:133], v219 offset:18432
	ds_read_b128 v[134:137], v220 offset:55296
	ds_read_b128 v[138:141], v219 offset:23040
	ds_read_b128 v[142:145], v219 offset:18464
	ds_read_b128 v[146:149], v220 offset:55328
	ds_read_b128 v[150:153], v219 offset:23072
	ds_read_b128 v[154:157], v219 offset:18496
	ds_read_b128 v[158:161], v220 offset:55360
	ds_read_b128 v[162:165], v219 offset:23104
	ds_read_b128 v[166:169], v219 offset:18528
	ds_read_b128 v[170:173], v220 offset:55392
	ds_read_b128 v[174:177], v219 offset:23136
	s_waitcnt lgkmcnt(10)
	v_mfma_f32_32x32x16_bf16 v[18:33], v[130:133], v[134:137], v[18:33]
	s_waitcnt lgkmcnt(9)
	v_mfma_f32_32x32x16_bf16 v[2:17], v[138:141], v[134:137], v[2:17]
	s_waitcnt lgkmcnt(7)
	v_mfma_f32_32x32x16_bf16 v[18:33], v[142:145], v[146:149], v[18:33]
	s_waitcnt lgkmcnt(6)
	v_mfma_f32_32x32x16_bf16 v[2:17], v[150:153], v[146:149], v[2:17]
	s_waitcnt lgkmcnt(4)
	v_mfma_f32_32x32x16_bf16 v[18:33], v[154:157], v[158:161], v[18:33]
	s_waitcnt lgkmcnt(3)
	v_mfma_f32_32x32x16_bf16 v[2:17], v[162:165], v[158:161], v[2:17]
	s_waitcnt lgkmcnt(1)
	v_mfma_f32_32x32x16_bf16 v[18:33], v[166:169], v[170:173], v[18:33]
	s_waitcnt lgkmcnt(0)
	v_mfma_f32_32x32x16_bf16 v[2:17], v[174:177], v[170:173], v[2:17]
	s_waitcnt vmcnt(20)
	ds_write_b128 v218, v[98:101]
	ds_write_b128 v218, v[102:105] offset:9216
	ds_write_b128 v218, v[106:109] offset:36864
	ds_write_b128 v218, v[110:113] offset:46080
	s_mul_i32 s52, s58, 0x300
	s_add_u32 s0, s22, s52
	s_addc_u32 s1, s23, 0
	s_add_u32 s2, s0, 0xc000
	s_addc_u32 s3, s1, 0
	s_mul_i32 s52, s59, 0x300
	s_add_u32 s4, s38, s52
	s_addc_u32 s5, s39, 0
	s_add_u32 s6, s4, 0xc000
	s_addc_u32 s7, s5, 0
	global_load_dwordx4 v[98:101], v212, s[0:1]
	global_load_dwordx4 v[102:105], v212, s[2:3]
	global_load_dwordx4 v[106:109], v216, s[4:5]
	global_load_dwordx4 v[110:113], v216, s[6:7]
	s_waitcnt lgkmcnt(0)
	s_barrier
; DI float bflo(unsigned w) { return __uint_as_float(w << 16); }
; DI float bfhi(unsigned w) { return __uint_as_float(w & 0xffff0000u); }
; template <bool RFA, bool RFB, class LA, class LB, class EPI>
; DI void gemm_tile2s(u16* smem, int nk, LA la, LB lb, EPI epi) {
;     ...
;   for (int kt = 0; kt < nk; kt += 2) {
;     compute(0);
;     if (kt + 1 < nk) { stl(ra1, rb1, 1); if (kt + 3 < nk) ld(ra1, rb1, kt + 3); }
;     __syncthreads();
;     if (kt + 1 < nk) {
;       compute(1);
;       if (kt + 2 < nk) { stl(ra0, rb0, 0); if (kt + 4 < nk) ld(ra0, rb0, kt + 4); }
;       __syncthreads();
; template <class ACC>
; DI void merge_branch(const Prm& p, u16* smem, const u16* W, const u16* X, int ld, int bi, int n0, int m0, ACC& macc) {
;     ...
;   auto epi = [&](f32x16 (&acc)[2], int wm, int wn, int lane) __attribute__((always_inline)) {
;     const int lr = lane & 31, lh = lane >> 5;
;     const int tok = m0 + wn * 32 + lr;
; #pragma unroll
;     for (int i = 0; i < 2; ++i)
; #pragma unroll
;       for (int h2 = 0; h2 < 2; ++h2) {
;         const int n = n0 + wm * 64 + i * 32 + 16 * lh + 8 * h2;
;         const u32x4 gz = *(const u32x4*)(p.zg + (size_t)tok * 4096 + bi * 1024 + n);
; #pragma unroll
;         for (int e = 0; e < 4; ++e) {
;           macc[i][8 * h2 + 2 * e] += bflo(gz[e]) * acc[i][8 * h2 + 2 * e];
;           macc[i][8 * h2 + 2 * e + 1] += bfhi(gz[e]) * acc[i][8 * h2 + 2 * e + 1];
;         }
;       }
;   };
	ds_read_b128 v[130:133], v219
	ds_read_b128 v[134:137], v220 offset:36864
	ds_read_b128 v[138:141], v219 offset:4608
	ds_read_b128 v[142:145], v219 offset:32
	ds_read_b128 v[146:149], v220 offset:36896
	ds_read_b128 v[150:153], v219 offset:4640
	ds_read_b128 v[154:157], v219 offset:64
	ds_read_b128 v[158:161], v220 offset:36928
	ds_read_b128 v[162:165], v219 offset:4672
	ds_read_b128 v[166:169], v219 offset:96
	ds_read_b128 v[170:173], v220 offset:36960
	ds_read_b128 v[174:177], v219 offset:4704
	s_waitcnt lgkmcnt(10)
	v_mfma_f32_32x32x16_bf16 v[18:33], v[130:133], v[134:137], v[18:33]
	s_waitcnt lgkmcnt(9)
	v_mfma_f32_32x32x16_bf16 v[2:17], v[138:141], v[134:137], v[2:17]
	s_waitcnt lgkmcnt(7)
	v_mfma_f32_32x32x16_bf16 v[18:33], v[142:145], v[146:149], v[18:33]
	s_waitcnt lgkmcnt(6)
	v_mfma_f32_32x32x16_bf16 v[2:17], v[150:153], v[146:149], v[2:17]
	s_waitcnt lgkmcnt(4)
	v_mfma_f32_32x32x16_bf16 v[18:33], v[154:157], v[158:161], v[18:33]
	s_waitcnt lgkmcnt(3)
	v_mfma_f32_32x32x16_bf16 v[2:17], v[162:165], v[158:161], v[2:17]
	s_waitcnt lgkmcnt(1)
	v_mfma_f32_32x32x16_bf16 v[18:33], v[166:169], v[170:173], v[18:33]
	s_waitcnt lgkmcnt(0)
	v_mfma_f32_32x32x16_bf16 v[2:17], v[174:177], v[170:173], v[2:17]
	s_waitcnt vmcnt(16)
	ds_write_b128 v218, v[114:117] offset:18432
	ds_write_b128 v218, v[118:121] offset:27648
	ds_write_b128 v218, v[122:125] offset:55296
	ds_write_b128 v218, v[126:129] offset:64512
	global_load_dwordx4 v[114:117], v212, s[0:1] offset:128
	global_load_dwordx4 v[118:121], v212, s[2:3] offset:128
	global_load_dwordx4 v[122:125], v216, s[4:5] offset:128
	global_load_dwordx4 v[126:129], v216, s[6:7] offset:128
	s_waitcnt lgkmcnt(0)
	s_barrier
	ds_read_b128 v[130:133], v219 offset:18432
	ds_read_b128 v[134:137], v220 offset:55296
	ds_read_b128 v[138:141], v219 offset:23040
	ds_read_b128 v[142:145], v219 offset:18464
	ds_read_b128 v[146:149], v220 offset:55328
	ds_read_b128 v[150:153], v219 offset:23072
	ds_read_b128 v[154:157], v219 offset:18496
	ds_read_b128 v[158:161], v220 offset:55360
	ds_read_b128 v[162:165], v219 offset:23104
	ds_read_b128 v[166:169], v219 offset:18528
	ds_read_b128 v[170:173], v220 offset:55392
	ds_read_b128 v[174:177], v219 offset:23136
	s_waitcnt lgkmcnt(10)
	v_mfma_f32_32x32x16_bf16 v[18:33], v[130:133], v[134:137], v[18:33]
	s_waitcnt lgkmcnt(9)
	v_mfma_f32_32x32x16_bf16 v[2:17], v[138:141], v[134:137], v[2:17]
	s_waitcnt lgkmcnt(7)
	v_mfma_f32_32x32x16_bf16 v[18:33], v[142:145], v[146:149], v[18:33]
	s_waitcnt lgkmcnt(6)
	v_mfma_f32_32x32x16_bf16 v[2:17], v[150:153], v[146:149], v[2:17]
	s_waitcnt lgkmcnt(4)
	v_mfma_f32_32x32x16_bf16 v[18:33], v[154:157], v[158:161], v[18:33]
	s_waitcnt lgkmcnt(3)
	v_mfma_f32_32x32x16_bf16 v[2:17], v[162:165], v[158:161], v[2:17]
	s_waitcnt lgkmcnt(1)
	v_mfma_f32_32x32x16_bf16 v[18:33], v[166:169], v[170:173], v[18:33]
	s_waitcnt lgkmcnt(0)
	v_mfma_f32_32x32x16_bf16 v[2:17], v[174:177], v[170:173], v[2:17]
	s_waitcnt vmcnt(24)
	s_nop 15
	v_lshlrev_b32_e32 v226, 16, v178
	v_and_b32_e32 v227, 0xffff0000, v178
	v_pk_mul_f32 v[34:35], v[226:227], v[18:19]
	v_lshlrev_b32_e32 v228, 16, v179
	v_and_b32_e32 v229, 0xffff0000, v179
	v_pk_mul_f32 v[36:37], v[228:229], v[20:21]
	v_lshlrev_b32_e32 v234, 16, v180
	v_and_b32_e32 v235, 0xffff0000, v180
	v_pk_mul_f32 v[38:39], v[234:235], v[22:23]
	v_lshlrev_b32_e32 v236, 16, v181
	v_and_b32_e32 v237, 0xffff0000, v181
	v_pk_mul_f32 v[40:41], v[236:237], v[24:25]
	v_lshlrev_b32_e32 v226, 16, v182
	v_and_b32_e32 v227, 0xffff0000, v182
	v_pk_mul_f32 v[42:43], v[226:227], v[26:27]
	v_lshlrev_b32_e32 v228, 16, v183
	v_and_b32_e32 v229, 0xffff0000, v183
	v_pk_mul_f32 v[44:45], v[228:229], v[28:29]
	v_lshlrev_b32_e32 v234, 16, v184
	v_and_b32_e32 v235, 0xffff0000, v184
	v_pk_mul_f32 v[46:47], v[234:235], v[30:31]
	v_lshlrev_b32_e32 v236, 16, v185
	v_and_b32_e32 v237, 0xffff0000, v185
	v_pk_mul_f32 v[48:49], v[236:237], v[32:33]
	v_lshlrev_b32_e32 v226, 16, v186
	v_and_b32_e32 v227, 0xffff0000, v186
	v_pk_mul_f32 v[50:51], v[226:227], v[2:3]
	v_lshlrev_b32_e32 v228, 16, v187
	v_and_b32_e32 v229, 0xffff0000, v187
	v_pk_mul_f32 v[52:53], v[228:229], v[4:5]
	v_lshlrev_b32_e32 v234, 16, v188
	v_and_b32_e32 v235, 0xffff0000, v188
	v_pk_mul_f32 v[54:55], v[234:235], v[6:7]
	v_lshlrev_b32_e32 v236, 16, v189
	v_and_b32_e32 v237, 0xffff0000, v189
	v_pk_mul_f32 v[56:57], v[236:237], v[8:9]
	v_lshlrev_b32_e32 v226, 16, v190
	v_and_b32_e32 v227, 0xffff0000, v190
	v_pk_mul_f32 v[58:59], v[226:227], v[10:11]
	v_lshlrev_b32_e32 v228, 16, v191
	v_and_b32_e32 v229, 0xffff0000, v191
	v_pk_mul_f32 v[60:61], v[228:229], v[12:13]
	v_lshlrev_b32_e32 v234, 16, v192
	v_and_b32_e32 v235, 0xffff0000, v192
	v_pk_mul_f32 v[62:63], v[234:235], v[14:15]
	v_lshlrev_b32_e32 v236, 16, v193
	v_and_b32_e32 v237, 0xffff0000, v193
	v_pk_mul_f32 v[64:65], v[236:237], v[16:17]
	s_waitcnt vmcnt(16)
	ds_write_b128 v218, v[66:69]
	ds_write_b128 v218, v[70:73] offset:9216
	ds_write_b128 v218, v[74:77] offset:36864
	ds_write_b128 v218, v[78:81] offset:46080
	global_load_dwordx4 v[66:69], v212, s[0:1] offset:256
	global_load_dwordx4 v[70:73], v212, s[2:3] offset:256
	global_load_dwordx4 v[74:77], v216, s[4:5] offset:256
	global_load_dwordx4 v[78:81], v216, s[6:7] offset:256
	s_waitcnt lgkmcnt(0)
	s_barrier
; DI float bflo(unsigned w) { return __uint_as_float(w << 16); }
; DI float bfhi(unsigned w) { return __uint_as_float(w & 0xffff0000u); }
; template <bool RFA, bool RFB, class LA, class LB, class EPI>
; DI void gemm_tile2s(u16* smem, int nk, LA la, LB lb, EPI epi) {
;     ...
;   for (int kt = 0; kt < nk; kt += 2) {
;     compute(0);
;     if (kt + 1 < nk) { stl(ra1, rb1, 1); if (kt + 3 < nk) ld(ra1, rb1, kt + 3); }
;     __syncthreads();
;     if (kt + 1 < nk) {
;       compute(1);
;       if (kt + 2 < nk) { stl(ra0, rb0, 0); if (kt + 4 < nk) ld(ra0, rb0, kt + 4); }
;       __syncthreads();
; template <class ACC>
; DI void merge_branch(const Prm& p, u16* smem, const u16* W, const u16* X, int ld, int bi, int n0, int m0, ACC& macc) {
;     ...
;   auto epi = [&](f32x16 (&acc)[2], int wm, int wn, int lane) __attribute__((always_inline)) {
;     const int lr = lane & 31, lh = lane >> 5;
;     const int tok = m0 + wn * 32 + lr;
; #pragma unroll
;     for (int i = 0; i < 2; ++i)
; #pragma unroll
;       for (int h2 = 0; h2 < 2; ++h2) {
;         const int n = n0 + wm * 64 + i * 32 + 16 * lh + 8 * h2;
;         const u32x4 gz = *(const u32x4*)(p.zg + (size_t)tok * 4096 + bi * 1024 + n);
; #pragma unroll
;         for (int e = 0; e < 4; ++e) {
;           macc[i][8 * h2 + 2 * e] += bflo(gz[e]) * acc[i][8 * h2 + 2 * e];
;           macc[i][8 * h2 + 2 * e + 1] += bfhi(gz[e]) * acc[i][8 * h2 + 2 * e + 1];
;         }
;       }
;   };
	ds_read_b128 v[130:133], v219
	ds_read_b128 v[134:137], v220 offset:36864
	ds_read_b128 v[138:141], v219 offset:4608
	ds_read_b128 v[142:145], v219 offset:32
	ds_read_b128 v[146:149], v220 offset:36896
	ds_read_b128 v[150:153], v219 offset:4640
	ds_read_b128 v[154:157], v219 offset:64
	ds_read_b128 v[158:161], v220 offset:36928
	ds_read_b128 v[162:165], v219 offset:4672
	ds_read_b128 v[166:169], v219 offset:96
	ds_read_b128 v[170:173], v220 offset:36960
	ds_read_b128 v[174:177], v219 offset:4704
	s_waitcnt lgkmcnt(10)
	v_mfma_f32_32x32x16_bf16 v[18:33], v[130:133], v[134:137], 0
	s_waitcnt lgkmcnt(9)
	v_mfma_f32_32x32x16_bf16 v[2:17], v[138:141], v[134:137], 0
	s_waitcnt lgkmcnt(7)
	v_mfma_f32_32x32x16_bf16 v[18:33], v[142:145], v[146:149], v[18:33]
	s_waitcnt lgkmcnt(6)
	v_mfma_f32_32x32x16_bf16 v[2:17], v[150:153], v[146:149], v[2:17]
	s_waitcnt lgkmcnt(4)
	v_mfma_f32_32x32x16_bf16 v[18:33], v[154:157], v[158:161], v[18:33]
	s_waitcnt lgkmcnt(3)
	v_mfma_f32_32x32x16_bf16 v[2:17], v[162:165], v[158:161], v[2:17]
	s_waitcnt lgkmcnt(1)
	v_mfma_f32_32x32x16_bf16 v[18:33], v[166:169], v[170:173], v[18:33]
	s_waitcnt lgkmcnt(0)
	v_mfma_f32_32x32x16_bf16 v[2:17], v[174:177], v[170:173], v[2:17]
	s_waitcnt vmcnt(12)
	ds_write_b128 v218, v[82:85] offset:18432
	ds_write_b128 v218, v[86:89] offset:27648
	ds_write_b128 v218, v[90:93] offset:55296
	ds_write_b128 v218, v[94:97] offset:64512
	global_load_dwordx4 v[82:85], v212, s[0:1] offset:384
	global_load_dwordx4 v[86:89], v212, s[2:3] offset:384
	global_load_dwordx4 v[90:93], v216, s[4:5] offset:384
	global_load_dwordx4 v[94:97], v216, s[6:7] offset:384
	global_load_dwordx4 v[178:181], v221, s[10:11]
	global_load_dwordx4 v[182:185], v221, s[10:11] offset:16
	global_load_dwordx4 v[186:189], v221, s[10:11] offset:64
	global_load_dwordx4 v[190:193], v221, s[10:11] offset:80
	s_waitcnt lgkmcnt(0)
	s_barrier
	ds_read_b128 v[130:133], v219 offset:18432
	ds_read_b128 v[134:137], v220 offset:55296
	ds_read_b128 v[138:141], v219 offset:23040
	ds_read_b128 v[142:145], v219 offset:18464
	ds_read_b128 v[146:149], v220 offset:55328
	ds_read_b128 v[150:153], v219 offset:23072
	ds_read_b128 v[154:157], v219 offset:18496
	ds_read_b128 v[158:161], v220 offset:55360
	ds_read_b128 v[162:165], v219 offset:23104
	ds_read_b128 v[166:169], v219 offset:18528
	ds_read_b128 v[170:173], v220 offset:55392
	ds_read_b128 v[174:177], v219 offset:23136
	s_waitcnt lgkmcnt(10)
	v_mfma_f32_32x32x16_bf16 v[18:33], v[130:133], v[134:137], v[18:33]
	s_waitcnt lgkmcnt(9)
	v_mfma_f32_32x32x16_bf16 v[2:17], v[138:141], v[134:137], v[2:17]
	s_waitcnt lgkmcnt(7)
	v_mfma_f32_32x32x16_bf16 v[18:33], v[142:145], v[146:149], v[18:33]
	s_waitcnt lgkmcnt(6)
	v_mfma_f32_32x32x16_bf16 v[2:17], v[150:153], v[146:149], v[2:17]
	s_waitcnt lgkmcnt(4)
	v_mfma_f32_32x32x16_bf16 v[18:33], v[154:157], v[158:161], v[18:33]
	s_waitcnt lgkmcnt(3)
	v_mfma_f32_32x32x16_bf16 v[2:17], v[162:165], v[158:161], v[2:17]
	s_waitcnt lgkmcnt(1)
	v_mfma_f32_32x32x16_bf16 v[18:33], v[166:169], v[170:173], v[18:33]
	s_waitcnt lgkmcnt(0)
	v_mfma_f32_32x32x16_bf16 v[2:17], v[174:177], v[170:173], v[2:17]
	s_waitcnt vmcnt(24)
	s_nop 15
	v_lshlrev_b32_e32 v226, 16, v194
	v_and_b32_e32 v227, 0xffff0000, v194
	v_pk_fma_f32 v[34:35], v[226:227], v[18:19], v[34:35]
	v_lshlrev_b32_e32 v228, 16, v195
	v_and_b32_e32 v229, 0xffff0000, v195
	v_pk_fma_f32 v[36:37], v[228:229], v[20:21], v[36:37]
	v_lshlrev_b32_e32 v234, 16, v196
	v_and_b32_e32 v235, 0xffff0000, v196
	v_pk_fma_f32 v[38:39], v[234:235], v[22:23], v[38:39]
	v_lshlrev_b32_e32 v236, 16, v197
	v_and_b32_e32 v237, 0xffff0000, v197
	v_pk_fma_f32 v[40:41], v[236:237], v[24:25], v[40:41]
	v_lshlrev_b32_e32 v226, 16, v198
	v_and_b32_e32 v227, 0xffff0000, v198
	v_pk_fma_f32 v[42:43], v[226:227], v[26:27], v[42:43]
	v_lshlrev_b32_e32 v228, 16, v199
	v_and_b32_e32 v229, 0xffff0000, v199
	v_pk_fma_f32 v[44:45], v[228:229], v[28:29], v[44:45]
	v_lshlrev_b32_e32 v234, 16, v200
	v_and_b32_e32 v235, 0xffff0000, v200
	v_pk_fma_f32 v[46:47], v[234:235], v[30:31], v[46:47]
	v_lshlrev_b32_e32 v236, 16, v201
	v_and_b32_e32 v237, 0xffff0000, v201
	v_pk_fma_f32 v[48:49], v[236:237], v[32:33], v[48:49]
	v_lshlrev_b32_e32 v226, 16, v202
	v_and_b32_e32 v227, 0xffff0000, v202
	v_pk_fma_f32 v[50:51], v[226:227], v[2:3], v[50:51]
	v_lshlrev_b32_e32 v228, 16, v203
	v_and_b32_e32 v229, 0xffff0000, v203
	v_pk_fma_f32 v[52:53], v[228:229], v[4:5], v[52:53]
	v_lshlrev_b32_e32 v234, 16, v204
	v_and_b32_e32 v235, 0xffff0000, v204
	v_pk_fma_f32 v[54:55], v[234:235], v[6:7], v[54:55]
	v_lshlrev_b32_e32 v236, 16, v205
	v_and_b32_e32 v237, 0xffff0000, v205
	v_pk_fma_f32 v[56:57], v[236:237], v[8:9], v[56:57]
	v_lshlrev_b32_e32 v226, 16, v206
	v_and_b32_e32 v227, 0xffff0000, v206
	v_pk_fma_f32 v[58:59], v[226:227], v[10:11], v[58:59]
	v_lshlrev_b32_e32 v228, 16, v207
	v_and_b32_e32 v229, 0xffff0000, v207
	v_pk_fma_f32 v[60:61], v[228:229], v[12:13], v[60:61]
	v_lshlrev_b32_e32 v234, 16, v208
	v_and_b32_e32 v235, 0xffff0000, v208
	v_pk_fma_f32 v[62:63], v[234:235], v[14:15], v[62:63]
	v_lshlrev_b32_e32 v236, 16, v209
	v_and_b32_e32 v237, 0xffff0000, v209
	v_pk_fma_f32 v[64:65], v[236:237], v[16:17], v[64:65]
	s_waitcnt vmcnt(16)
	ds_write_b128 v218, v[98:101]
	ds_write_b128 v218, v[102:105] offset:9216
	ds_write_b128 v218, v[106:109] offset:36864
	ds_write_b128 v218, v[110:113] offset:46080
	global_load_dwordx4 v[98:101], v212, s[0:1] offset:512
	global_load_dwordx4 v[102:105], v212, s[2:3] offset:512
	global_load_dwordx4 v[106:109], v216, s[4:5] offset:512
	global_load_dwordx4 v[110:113], v216, s[6:7] offset:512
	s_waitcnt lgkmcnt(0)
	s_barrier
; template <bool RFA, bool RFB, class LA, class LB, class EPI>
; DI void gemm_tile2s(u16* smem, int nk, LA la, LB lb, EPI epi) {
;     ...
;   for (int kt = 0; kt < nk; kt += 2) {
;     compute(0);
;     if (kt + 1 < nk) { stl(ra1, rb1, 1); if (kt + 3 < nk) ld(ra1, rb1, kt + 3); }
;     __syncthreads();
;     if (kt + 1 < nk) {
;       compute(1);
;       if (kt + 2 < nk) { stl(ra0, rb0, 0); if (kt + 4 < nk) ld(ra0, rb0, kt + 4); }
;       __syncthreads();
; DI void phase_merge(const Prm& p, u16* smem, int l, int& base) {
;     ...
;     merge_branch(p, smem, p.PaT + (size_t)l * 1024 * 768, p.UT, 768, 0, n0, m0, macc);
;     merge_branch(p, smem, p.PbT + (size_t)l * 1024 * 128, p.ob, 128, 1, n0, m0, macc);
;     ...
;     merge_branch(p, smem, p.PdT + (size_t)l * 1024 * 256, p.od, 256, 3, n0, m0, macc);
	ds_read_b128 v[130:133], v219
	ds_read_b128 v[134:137], v220 offset:36864
	ds_read_b128 v[138:141], v219 offset:4608
	ds_read_b128 v[142:145], v219 offset:32
	ds_read_b128 v[146:149], v220 offset:36896
	ds_read_b128 v[150:153], v219 offset:4640
	ds_read_b128 v[154:157], v219 offset:64
	ds_read_b128 v[158:161], v220 offset:36928
	ds_read_b128 v[162:165], v219 offset:4672
	ds_read_b128 v[166:169], v219 offset:96
	ds_read_b128 v[170:173], v220 offset:36960
	ds_read_b128 v[174:177], v219 offset:4704
	s_waitcnt lgkmcnt(10)
	v_mfma_f32_32x32x16_bf16 v[18:33], v[130:133], v[134:137], 0
	s_waitcnt lgkmcnt(9)
	v_mfma_f32_32x32x16_bf16 v[2:17], v[138:141], v[134:137], 0
	s_waitcnt lgkmcnt(7)
	v_mfma_f32_32x32x16_bf16 v[18:33], v[142:145], v[146:149], v[18:33]
	s_waitcnt lgkmcnt(6)
	v_mfma_f32_32x32x16_bf16 v[2:17], v[150:153], v[146:149], v[2:17]
	s_waitcnt lgkmcnt(4)
	v_mfma_f32_32x32x16_bf16 v[18:33], v[154:157], v[158:161], v[18:33]
	s_waitcnt lgkmcnt(3)
	v_mfma_f32_32x32x16_bf16 v[2:17], v[162:165], v[158:161], v[2:17]
	s_waitcnt lgkmcnt(1)
	v_mfma_f32_32x32x16_bf16 v[18:33], v[166:169], v[170:173], v[18:33]
	s_waitcnt lgkmcnt(0)
	v_mfma_f32_32x32x16_bf16 v[2:17], v[174:177], v[170:173], v[2:17]
	s_waitcnt vmcnt(16)
	ds_write_b128 v218, v[114:117] offset:18432
	ds_write_b128 v218, v[118:121] offset:27648
	ds_write_b128 v218, v[122:125] offset:55296
	ds_write_b128 v218, v[126:129] offset:64512
	global_load_dwordx4 v[114:117], v212, s[0:1] offset:640
	global_load_dwordx4 v[118:121], v212, s[2:3] offset:640
	global_load_dwordx4 v[122:125], v216, s[4:5] offset:640
	global_load_dwordx4 v[126:129], v216, s[6:7] offset:640
	global_load_dwordx4 v[194:197], v221, s[10:11] offset:2048
	global_load_dwordx4 v[198:201], v221, s[10:11] offset:2064
	global_load_dwordx4 v[202:205], v221, s[10:11] offset:2112
	global_load_dwordx4 v[206:209], v221, s[10:11] offset:2128
	s_waitcnt lgkmcnt(0)
	s_barrier
	ds_read_b128 v[130:133], v219 offset:18432
	ds_read_b128 v[134:137], v220 offset:55296
	ds_read_b128 v[138:141], v219 offset:23040
	ds_read_b128 v[142:145], v219 offset:18464
	ds_read_b128 v[146:149], v220 offset:55328
	ds_read_b128 v[150:153], v219 offset:23072
	ds_read_b128 v[154:157], v219 offset:18496
	ds_read_b128 v[158:161], v220 offset:55360
	ds_read_b128 v[162:165], v219 offset:23104
	ds_read_b128 v[166:169], v219 offset:18528
	ds_read_b128 v[170:173], v220 offset:55392
	ds_read_b128 v[174:177], v219 offset:23136
	s_waitcnt lgkmcnt(10)
	v_mfma_f32_32x32x16_bf16 v[18:33], v[130:133], v[134:137], v[18:33]
	s_waitcnt lgkmcnt(9)
	v_mfma_f32_32x32x16_bf16 v[2:17], v[138:141], v[134:137], v[2:17]
	s_waitcnt lgkmcnt(7)
	v_mfma_f32_32x32x16_bf16 v[18:33], v[142:145], v[146:149], v[18:33]
	s_waitcnt lgkmcnt(6)
	v_mfma_f32_32x32x16_bf16 v[2:17], v[150:153], v[146:149], v[2:17]
	s_waitcnt lgkmcnt(4)
	v_mfma_f32_32x32x16_bf16 v[18:33], v[154:157], v[158:161], v[18:33]
	s_waitcnt lgkmcnt(3)
	v_mfma_f32_32x32x16_bf16 v[2:17], v[162:165], v[158:161], v[2:17]
	s_waitcnt lgkmcnt(1)
	v_mfma_f32_32x32x16_bf16 v[18:33], v[166:169], v[170:173], v[18:33]
	s_waitcnt lgkmcnt(0)
	v_mfma_f32_32x32x16_bf16 v[2:17], v[174:177], v[170:173], v[2:17]
	s_waitcnt vmcnt(20)
	ds_write_b128 v218, v[66:69]
	ds_write_b128 v218, v[70:73] offset:9216
	ds_write_b128 v218, v[74:77] offset:36864
	ds_write_b128 v218, v[78:81] offset:46080
	s_mul_i32 s52, s58, 0x200
	s_add_u32 s0, s44, s52
	s_addc_u32 s1, s45, 0
	s_add_u32 s2, s0, 0x8000
	s_addc_u32 s3, s1, 0
	s_mul_i32 s52, s59, 0x200
	s_add_u32 s4, s40, s52
	s_addc_u32 s5, s41, 0
	s_add_u32 s6, s4, 0x8000
	s_addc_u32 s7, s5, 0
	global_load_dwordx4 v[66:69], v213, s[0:1]
	global_load_dwordx4 v[70:73], v213, s[2:3]
	global_load_dwordx4 v[74:77], v217, s[4:5]
	global_load_dwordx4 v[78:81], v217, s[6:7]
	s_waitcnt lgkmcnt(0)
	s_barrier
	ds_read_b128 v[130:133], v219
	ds_read_b128 v[134:137], v220 offset:36864
	ds_read_b128 v[138:141], v219 offset:4608
	ds_read_b128 v[142:145], v219 offset:32
	ds_read_b128 v[146:149], v220 offset:36896
	ds_read_b128 v[150:153], v219 offset:4640
	ds_read_b128 v[154:157], v219 offset:64
	ds_read_b128 v[158:161], v220 offset:36928
	ds_read_b128 v[162:165], v219 offset:4672
	ds_read_b128 v[166:169], v219 offset:96
	ds_read_b128 v[170:173], v220 offset:36960
	ds_read_b128 v[174:177], v219 offset:4704
	s_waitcnt lgkmcnt(10)
	v_mfma_f32_32x32x16_bf16 v[18:33], v[130:133], v[134:137], v[18:33]
	s_waitcnt lgkmcnt(9)
	v_mfma_f32_32x32x16_bf16 v[2:17], v[138:141], v[134:137], v[2:17]
	s_waitcnt lgkmcnt(7)
	v_mfma_f32_32x32x16_bf16 v[18:33], v[142:145], v[146:149], v[18:33]
	s_waitcnt lgkmcnt(6)
	v_mfma_f32_32x32x16_bf16 v[2:17], v[150:153], v[146:149], v[2:17]
	s_waitcnt lgkmcnt(4)
	v_mfma_f32_32x32x16_bf16 v[18:33], v[154:157], v[158:161], v[18:33]
	s_waitcnt lgkmcnt(3)
	v_mfma_f32_32x32x16_bf16 v[2:17], v[162:165], v[158:161], v[2:17]
	s_waitcnt lgkmcnt(1)
	v_mfma_f32_32x32x16_bf16 v[18:33], v[166:169], v[170:173], v[18:33]
	s_waitcnt lgkmcnt(0)
	v_mfma_f32_32x32x16_bf16 v[2:17], v[174:177], v[170:173], v[2:17]
	s_waitcnt vmcnt(20)
	ds_write_b128 v218, v[82:85] offset:18432
	ds_write_b128 v218, v[86:89] offset:27648
	ds_write_b128 v218, v[90:93] offset:55296
	ds_write_b128 v218, v[94:97] offset:64512
	global_load_dwordx4 v[82:85], v213, s[0:1] offset:128
	global_load_dwordx4 v[86:89], v213, s[2:3] offset:128
	global_load_dwordx4 v[90:93], v217, s[4:5] offset:128
	global_load_dwordx4 v[94:97], v217, s[6:7] offset:128
	s_waitcnt lgkmcnt(0)
	s_barrier
; template <bool RFA, bool RFB, class LA, class LB, class EPI>
; DI void gemm_tile2s(u16* smem, int nk, LA la, LB lb, EPI epi) {
;     ...
;   for (int kt = 0; kt < nk; kt += 2) {
;     compute(0);
;     if (kt + 1 < nk) { stl(ra1, rb1, 1); if (kt + 3 < nk) ld(ra1, rb1, kt + 3); }
;     __syncthreads();
;     if (kt + 1 < nk) {
;       compute(1);
;       if (kt + 2 < nk) { stl(ra0, rb0, 0); if (kt + 4 < nk) ld(ra0, rb0, kt + 4); }
;       __syncthreads();
	ds_read_b128 v[130:133], v219 offset:18432
	ds_read_b128 v[134:137], v220 offset:55296
	ds_read_b128 v[138:141], v219 offset:23040
	ds_read_b128 v[142:145], v219 offset:18464
	ds_read_b128 v[146:149], v220 offset:55328
	ds_read_b128 v[150:153], v219 offset:23072
	ds_read_b128 v[154:157], v219 offset:18496
	ds_read_b128 v[158:161], v220 offset:55360
	ds_read_b128 v[162:165], v219 offset:23104
	ds_read_b128 v[166:169], v219 offset:18528
	ds_read_b128 v[170:173], v220 offset:55392
	ds_read_b128 v[174:177], v219 offset:23136
	s_waitcnt lgkmcnt(10)
	v_mfma_f32_32x32x16_bf16 v[18:33], v[130:133], v[134:137], v[18:33]
	s_waitcnt lgkmcnt(9)
	v_mfma_f32_32x32x16_bf16 v[2:17], v[138:141], v[134:137], v[2:17]
	s_waitcnt lgkmcnt(7)
	v_mfma_f32_32x32x16_bf16 v[18:33], v[142:145], v[146:149], v[18:33]
	s_waitcnt lgkmcnt(6)
	v_mfma_f32_32x32x16_bf16 v[2:17], v[150:153], v[146:149], v[2:17]
	s_waitcnt lgkmcnt(4)
	v_mfma_f32_32x32x16_bf16 v[18:33], v[154:157], v[158:161], v[18:33]
	s_waitcnt lgkmcnt(3)
	v_mfma_f32_32x32x16_bf16 v[2:17], v[162:165], v[158:161], v[2:17]
	s_waitcnt lgkmcnt(1)
	v_mfma_f32_32x32x16_bf16 v[18:33], v[166:169], v[170:173], v[18:33]
	s_waitcnt lgkmcnt(0)
	v_mfma_f32_32x32x16_bf16 v[2:17], v[174:177], v[170:173], v[2:17]
	s_waitcnt vmcnt(16)
	ds_write_b128 v218, v[98:101]
	ds_write_b128 v218, v[102:105] offset:9216
	ds_write_b128 v218, v[106:109] offset:36864
	ds_write_b128 v218, v[110:113] offset:46080
	global_load_dwordx4 v[98:101], v213, s[0:1] offset:256
	global_load_dwordx4 v[102:105], v213, s[2:3] offset:256
	global_load_dwordx4 v[106:109], v217, s[4:5] offset:256
	global_load_dwordx4 v[110:113], v217, s[6:7] offset:256
	s_waitcnt lgkmcnt(0)
	s_barrier
	ds_read_b128 v[130:133], v219
	ds_read_b128 v[134:137], v220 offset:36864
	ds_read_b128 v[138:141], v219 offset:4608
	ds_read_b128 v[142:145], v219 offset:32
	ds_read_b128 v[146:149], v220 offset:36896
	ds_read_b128 v[150:153], v219 offset:4640
	ds_read_b128 v[154:157], v219 offset:64
	ds_read_b128 v[158:161], v220 offset:36928
	ds_read_b128 v[162:165], v219 offset:4672
	ds_read_b128 v[166:169], v219 offset:96
	ds_read_b128 v[170:173], v220 offset:36960
	ds_read_b128 v[174:177], v219 offset:4704
	s_waitcnt lgkmcnt(10)
	v_mfma_f32_32x32x16_bf16 v[18:33], v[130:133], v[134:137], v[18:33]
	s_waitcnt lgkmcnt(9)
	v_mfma_f32_32x32x16_bf16 v[2:17], v[138:141], v[134:137], v[2:17]
	s_waitcnt lgkmcnt(7)
	v_mfma_f32_32x32x16_bf16 v[18:33], v[142:145], v[146:149], v[18:33]
	s_waitcnt lgkmcnt(6)
	v_mfma_f32_32x32x16_bf16 v[2:17], v[150:153], v[146:149], v[2:17]
	s_waitcnt lgkmcnt(4)
	v_mfma_f32_32x32x16_bf16 v[18:33], v[154:157], v[158:161], v[18:33]
	s_waitcnt lgkmcnt(3)
	v_mfma_f32_32x32x16_bf16 v[2:17], v[162:165], v[158:161], v[2:17]
	s_waitcnt lgkmcnt(1)
	v_mfma_f32_32x32x16_bf16 v[18:33], v[166:169], v[170:173], v[18:33]
	s_waitcnt lgkmcnt(0)
	v_mfma_f32_32x32x16_bf16 v[2:17], v[174:177], v[170:173], v[2:17]
	s_waitcnt vmcnt(16)
	ds_write_b128 v218, v[114:117] offset:18432
	ds_write_b128 v218, v[118:121] offset:27648
	ds_write_b128 v218, v[122:125] offset:55296
	ds_write_b128 v218, v[126:129] offset:64512
	global_load_dwordx4 v[114:117], v213, s[0:1] offset:384
	global_load_dwordx4 v[118:121], v213, s[2:3] offset:384
	global_load_dwordx4 v[122:125], v217, s[4:5] offset:384
	global_load_dwordx4 v[126:129], v217, s[6:7] offset:384
	s_waitcnt lgkmcnt(0)
	s_barrier
	ds_read_b128 v[130:133], v219 offset:18432
	ds_read_b128 v[134:137], v220 offset:55296
	ds_read_b128 v[138:141], v219 offset:23040
	ds_read_b128 v[142:145], v219 offset:18464
	ds_read_b128 v[146:149], v220 offset:55328
	ds_read_b128 v[150:153], v219 offset:23072
	ds_read_b128 v[154:157], v219 offset:18496
	ds_read_b128 v[158:161], v220 offset:55360
	ds_read_b128 v[162:165], v219 offset:23104
	ds_read_b128 v[166:169], v219 offset:18528
	ds_read_b128 v[170:173], v220 offset:55392
	ds_read_b128 v[174:177], v219 offset:23136
	s_waitcnt lgkmcnt(10)
	v_mfma_f32_32x32x16_bf16 v[18:33], v[130:133], v[134:137], v[18:33]
	s_waitcnt lgkmcnt(9)
	v_mfma_f32_32x32x16_bf16 v[2:17], v[138:141], v[134:137], v[2:17]
	s_waitcnt lgkmcnt(7)
	v_mfma_f32_32x32x16_bf16 v[18:33], v[142:145], v[146:149], v[18:33]
	s_waitcnt lgkmcnt(6)
	v_mfma_f32_32x32x16_bf16 v[2:17], v[150:153], v[146:149], v[2:17]
	s_waitcnt lgkmcnt(4)
	v_mfma_f32_32x32x16_bf16 v[18:33], v[154:157], v[158:161], v[18:33]
	s_waitcnt lgkmcnt(3)
	v_mfma_f32_32x32x16_bf16 v[2:17], v[162:165], v[158:161], v[2:17]
	s_waitcnt lgkmcnt(1)
	v_mfma_f32_32x32x16_bf16 v[18:33], v[166:169], v[170:173], v[18:33]
	s_waitcnt lgkmcnt(0)
	v_mfma_f32_32x32x16_bf16 v[2:17], v[174:177], v[170:173], v[2:17]
	s_waitcnt vmcnt(28)
; DI float bflo(unsigned w) { return __uint_as_float(w << 16); }
; DI float bfhi(unsigned w) { return __uint_as_float(w & 0xffff0000u); }
; DI f32x16 zero16() { f32x16 z; for (int i = 0; i < 16; ++i) z[i] = 0.f; return z; }
; #define TASK_LOOP(t, nt, base) for (int t = (int)((blockIdx.x + gridDim.x - ((unsigned)(base) % gridDim.x)) % gridDim.x); t < (nt); t += gridDim.x)
; template <class ACC>
; DI void merge_branch(const Prm& p, u16* smem, const u16* W, const u16* X, int ld, int bi, int n0, int m0, ACC& macc) {
;     ...
;   auto epi = [&](f32x16 (&acc)[2], int wm, int wn, int lane) __attribute__((always_inline)) {
;     const int lr = lane & 31, lh = lane >> 5;
;     const int tok = m0 + wn * 32 + lr;
; #pragma unroll
;     for (int i = 0; i < 2; ++i)
; #pragma unroll
;       for (int h2 = 0; h2 < 2; ++h2) {
;         const int n = n0 + wm * 64 + i * 32 + 16 * lh + 8 * h2;
;         const u32x4 gz = *(const u32x4*)(p.zg + (size_t)tok * 4096 + bi * 1024 + n);
; #pragma unroll
;         for (int e = 0; e < 4; ++e) {
;           macc[i][8 * h2 + 2 * e] += bflo(gz[e]) * acc[i][8 * h2 + 2 * e];
;           macc[i][8 * h2 + 2 * e + 1] += bfhi(gz[e]) * acc[i][8 * h2 + 2 * e + 1];
;         }
; DI void phase_merge(const Prm& p, u16* smem, int l, int& base) {
;   TASK_LOOP(t, 8 * 128, base) {
;     const int tn = t & 7, tm = t >> 3, n0 = tn * 128, m0 = tm * 128;
;     f32x16 macc[2];
;     macc[0] = zero16(); macc[1] = zero16();
;     merge_branch(p, smem, p.PaT + (size_t)l * 1024 * 768, p.UT, 768, 0, n0, m0, macc);
;     merge_branch(p, smem, p.PbT + (size_t)l * 1024 * 128, p.ob, 128, 1, n0, m0, macc);
;     ...
;     merge_branch(p, smem, p.PdT + (size_t)l * 1024 * 256, p.od, 256, 3, n0, m0, macc);
	s_nop 15
	v_lshlrev_b32_e32 v226, 16, v178
	v_and_b32_e32 v227, 0xffff0000, v178
	v_pk_fma_f32 v[34:35], v[226:227], v[18:19], v[34:35]
	v_lshlrev_b32_e32 v228, 16, v179
	v_and_b32_e32 v229, 0xffff0000, v179
	v_pk_fma_f32 v[36:37], v[228:229], v[20:21], v[36:37]
	v_lshlrev_b32_e32 v234, 16, v180
	v_and_b32_e32 v235, 0xffff0000, v180
	v_pk_fma_f32 v[38:39], v[234:235], v[22:23], v[38:39]
	v_lshlrev_b32_e32 v236, 16, v181
	v_and_b32_e32 v237, 0xffff0000, v181
	v_pk_fma_f32 v[40:41], v[236:237], v[24:25], v[40:41]
	v_lshlrev_b32_e32 v226, 16, v182
	v_and_b32_e32 v227, 0xffff0000, v182
	v_pk_fma_f32 v[42:43], v[226:227], v[26:27], v[42:43]
	v_lshlrev_b32_e32 v228, 16, v183
	v_and_b32_e32 v229, 0xffff0000, v183
	v_pk_fma_f32 v[44:45], v[228:229], v[28:29], v[44:45]
	v_lshlrev_b32_e32 v234, 16, v184
	v_and_b32_e32 v235, 0xffff0000, v184
	v_pk_fma_f32 v[46:47], v[234:235], v[30:31], v[46:47]
	v_lshlrev_b32_e32 v236, 16, v185
	v_and_b32_e32 v237, 0xffff0000, v185
	v_pk_fma_f32 v[48:49], v[236:237], v[32:33], v[48:49]
	v_lshlrev_b32_e32 v226, 16, v186
	v_and_b32_e32 v227, 0xffff0000, v186
	v_pk_fma_f32 v[50:51], v[226:227], v[2:3], v[50:51]
	v_lshlrev_b32_e32 v228, 16, v187
	v_and_b32_e32 v229, 0xffff0000, v187
	v_pk_fma_f32 v[52:53], v[228:229], v[4:5], v[52:53]
	v_lshlrev_b32_e32 v234, 16, v188
	v_and_b32_e32 v235, 0xffff0000, v188
	v_pk_fma_f32 v[54:55], v[234:235], v[6:7], v[54:55]
	v_lshlrev_b32_e32 v236, 16, v189
	v_and_b32_e32 v237, 0xffff0000, v189
	v_pk_fma_f32 v[56:57], v[236:237], v[8:9], v[56:57]
	v_lshlrev_b32_e32 v226, 16, v190
	v_and_b32_e32 v227, 0xffff0000, v190
	v_pk_fma_f32 v[58:59], v[226:227], v[10:11], v[58:59]
	v_lshlrev_b32_e32 v228, 16, v191
	v_and_b32_e32 v229, 0xffff0000, v191
	v_pk_fma_f32 v[60:61], v[228:229], v[12:13], v[60:61]
	v_lshlrev_b32_e32 v234, 16, v192
	v_and_b32_e32 v235, 0xffff0000, v192
	v_pk_fma_f32 v[62:63], v[234:235], v[14:15], v[62:63]
	v_lshlrev_b32_e32 v236, 16, v193
	v_and_b32_e32 v237, 0xffff0000, v193
	v_pk_fma_f32 v[64:65], v[236:237], v[16:17], v[64:65]
	s_waitcnt vmcnt(12)
	ds_write_b128 v218, v[66:69]
	ds_write_b128 v218, v[70:73] offset:9216
	ds_write_b128 v218, v[74:77] offset:36864
	ds_write_b128 v218, v[78:81] offset:46080
	s_add_i32 s50, s31, s30
	s_cmpk_lt_i32 s50, 0x400
	s_cselect_b32 s50, s50, s31
	s_and_b32 s60, s50, 7
	s_lshl_b32 s60, s60, 7
	s_lshr_b32 s61, s50, 3
	s_lshl_b32 s61, s61, 7
	s_mul_i32 s52, s60, 0x600
	s_add_u32 s0, s16, s52
	s_addc_u32 s1, s17, 0
	s_add_u32 s2, s0, 0x18000
	s_addc_u32 s3, s1, 0
	s_mul_i32 s52, s61, 0x600
	s_add_u32 s4, s14, s52
	s_addc_u32 s5, s15, 0
	s_add_u32 s6, s4, 0x18000
	s_addc_u32 s7, s5, 0
	global_load_dwordx4 v[66:69], v210, s[0:1]
	global_load_dwordx4 v[70:73], v210, s[2:3]
	global_load_dwordx4 v[74:77], v214, s[4:5]
	global_load_dwordx4 v[78:81], v214, s[6:7]
	s_waitcnt lgkmcnt(0)
	s_barrier
	ds_read_b128 v[130:133], v219
	ds_read_b128 v[134:137], v220 offset:36864
	ds_read_b128 v[138:141], v219 offset:4608
	ds_read_b128 v[142:145], v219 offset:32
	ds_read_b128 v[146:149], v220 offset:36896
	ds_read_b128 v[150:153], v219 offset:4640
	ds_read_b128 v[154:157], v219 offset:64
	ds_read_b128 v[158:161], v220 offset:36928
	ds_read_b128 v[162:165], v219 offset:4672
	ds_read_b128 v[166:169], v219 offset:96
	ds_read_b128 v[170:173], v220 offset:36960
	ds_read_b128 v[174:177], v219 offset:4704
	s_waitcnt lgkmcnt(10)
	v_mfma_f32_32x32x16_bf16 v[18:33], v[130:133], v[134:137], 0
	s_waitcnt lgkmcnt(9)
	v_mfma_f32_32x32x16_bf16 v[2:17], v[138:141], v[134:137], 0
	s_waitcnt lgkmcnt(7)
	v_mfma_f32_32x32x16_bf16 v[18:33], v[142:145], v[146:149], v[18:33]
	s_waitcnt lgkmcnt(6)
	v_mfma_f32_32x32x16_bf16 v[2:17], v[150:153], v[146:149], v[2:17]
	s_waitcnt lgkmcnt(4)
	v_mfma_f32_32x32x16_bf16 v[18:33], v[154:157], v[158:161], v[18:33]
	s_waitcnt lgkmcnt(3)
	v_mfma_f32_32x32x16_bf16 v[2:17], v[162:165], v[158:161], v[2:17]
	s_waitcnt lgkmcnt(1)
	v_mfma_f32_32x32x16_bf16 v[18:33], v[166:169], v[170:173], v[18:33]
	s_waitcnt lgkmcnt(0)
	v_mfma_f32_32x32x16_bf16 v[2:17], v[174:177], v[170:173], v[2:17]
	s_waitcnt vmcnt(12)
	ds_write_b128 v218, v[82:85] offset:18432
	ds_write_b128 v218, v[86:89] offset:27648
	ds_write_b128 v218, v[90:93] offset:55296
	ds_write_b128 v218, v[94:97] offset:64512
	global_load_dwordx4 v[82:85], v210, s[0:1] offset:128
	global_load_dwordx4 v[86:89], v210, s[2:3] offset:128
	global_load_dwordx4 v[90:93], v214, s[4:5] offset:128
	global_load_dwordx4 v[94:97], v214, s[6:7] offset:128
	s_waitcnt lgkmcnt(0)
	s_barrier
	ds_read_b128 v[130:133], v219 offset:18432
	ds_read_b128 v[134:137], v220 offset:55296
	ds_read_b128 v[138:141], v219 offset:23040
	ds_read_b128 v[142:145], v219 offset:18464
	ds_read_b128 v[146:149], v220 offset:55328
	ds_read_b128 v[150:153], v219 offset:23072
	ds_read_b128 v[154:157], v219 offset:18496
	ds_read_b128 v[158:161], v220 offset:55360
	ds_read_b128 v[162:165], v219 offset:23104
	ds_read_b128 v[166:169], v219 offset:18528
	ds_read_b128 v[170:173], v220 offset:55392
	ds_read_b128 v[174:177], v219 offset:23136
	s_waitcnt lgkmcnt(10)
	v_mfma_f32_32x32x16_bf16 v[18:33], v[130:133], v[134:137], v[18:33]
	s_waitcnt lgkmcnt(9)
	v_mfma_f32_32x32x16_bf16 v[2:17], v[138:141], v[134:137], v[2:17]
	s_waitcnt lgkmcnt(7)
	v_mfma_f32_32x32x16_bf16 v[18:33], v[142:145], v[146:149], v[18:33]
	s_waitcnt lgkmcnt(6)
	v_mfma_f32_32x32x16_bf16 v[2:17], v[150:153], v[146:149], v[2:17]
	s_waitcnt lgkmcnt(4)
	v_mfma_f32_32x32x16_bf16 v[18:33], v[154:157], v[158:161], v[18:33]
	s_waitcnt lgkmcnt(3)
	v_mfma_f32_32x32x16_bf16 v[2:17], v[162:165], v[158:161], v[2:17]
	s_waitcnt lgkmcnt(1)
	v_mfma_f32_32x32x16_bf16 v[18:33], v[166:169], v[170:173], v[18:33]
	s_waitcnt lgkmcnt(0)
	v_mfma_f32_32x32x16_bf16 v[2:17], v[174:177], v[170:173], v[2:17]
	s_waitcnt vmcnt(12)
	ds_write_b128 v218, v[98:101]
	ds_write_b128 v218, v[102:105] offset:9216
	ds_write_b128 v218, v[106:109] offset:36864
	ds_write_b128 v218, v[110:113] offset:46080
	global_load_dwordx4 v[98:101], v210, s[0:1] offset:256
	global_load_dwordx4 v[102:105], v210, s[2:3] offset:256
	global_load_dwordx4 v[106:109], v214, s[4:5] offset:256
	global_load_dwordx4 v[110:113], v214, s[6:7] offset:256
	s_waitcnt lgkmcnt(0)
	s_barrier
; DI float bflo(unsigned w) { return __uint_as_float(w << 16); }
; DI float bfhi(unsigned w) { return __uint_as_float(w & 0xffff0000u); }
; DI int tidx() { int t = threadIdx.x; asm volatile("" : "+v"(t)); return t; }
; template <class ACC>
; DI void merge_branch(const Prm& p, u16* smem, const u16* W, const u16* X, int ld, int bi, int n0, int m0, ACC& macc) {
;     ...
;   auto epi = [&](f32x16 (&acc)[2], int wm, int wn, int lane) __attribute__((always_inline)) {
;     const int lr = lane & 31, lh = lane >> 5;
;     const int tok = m0 + wn * 32 + lr;
; #pragma unroll
;     for (int i = 0; i < 2; ++i)
; #pragma unroll
;       for (int h2 = 0; h2 < 2; ++h2) {
;         const int n = n0 + wm * 64 + i * 32 + 16 * lh + 8 * h2;
;         const u32x4 gz = *(const u32x4*)(p.zg + (size_t)tok * 4096 + bi * 1024 + n);
; #pragma unroll
;         for (int e = 0; e < 4; ++e) {
;           macc[i][8 * h2 + 2 * e] += bflo(gz[e]) * acc[i][8 * h2 + 2 * e];
;           macc[i][8 * h2 + 2 * e + 1] += bfhi(gz[e]) * acc[i][8 * h2 + 2 * e + 1];
;         }
; DI void phase_merge(const Prm& p, u16* smem, int l, int& base) {
;     ...
;     const int tid2 = tidx(), lane = tid2 & 63, wave = tid2 >> 6, wm = wave >> 2, wn = wave & 3, lr = lane & 31, lh = lane >> 5;
;     const int tok = m0 + wn * 32 + lr;
; #pragma unroll
;     for (int i = 0; i < 2; ++i)
; #pragma unroll
;       for (int h2 = 0; h2 < 2; ++h2) {
;         u32x4 o;
; #pragma unroll
;         for (int e = 0; e < 4; ++e) o[e] = pack2(macc[i][8 * h2 + 2 * e], macc[i][8 * h2 + 2 * e + 1]);
;         *(u32x4*)(p.hbuf + (size_t)tok * 1024 + n0 + wm * 64 + i * 32 + 16 * lh + 8 * h2) = o;
;       }
	ds_read_b128 v[130:133], v219
	ds_read_b128 v[134:137], v220 offset:36864
	ds_read_b128 v[138:141], v219 offset:4608
	ds_read_b128 v[142:145], v219 offset:32
	ds_read_b128 v[146:149], v220 offset:36896
	ds_read_b128 v[150:153], v219 offset:4640
	ds_read_b128 v[154:157], v219 offset:64
	ds_read_b128 v[158:161], v220 offset:36928
	ds_read_b128 v[162:165], v219 offset:4672
	ds_read_b128 v[166:169], v219 offset:96
	ds_read_b128 v[170:173], v220 offset:36960
	ds_read_b128 v[174:177], v219 offset:4704
	s_waitcnt lgkmcnt(10)
	v_mfma_f32_32x32x16_bf16 v[18:33], v[130:133], v[134:137], v[18:33]
	s_waitcnt lgkmcnt(9)
	v_mfma_f32_32x32x16_bf16 v[2:17], v[138:141], v[134:137], v[2:17]
	s_waitcnt lgkmcnt(7)
	v_mfma_f32_32x32x16_bf16 v[18:33], v[142:145], v[146:149], v[18:33]
	s_waitcnt lgkmcnt(6)
	v_mfma_f32_32x32x16_bf16 v[2:17], v[150:153], v[146:149], v[2:17]
	s_waitcnt lgkmcnt(4)
	v_mfma_f32_32x32x16_bf16 v[18:33], v[154:157], v[158:161], v[18:33]
	s_waitcnt lgkmcnt(3)
	v_mfma_f32_32x32x16_bf16 v[2:17], v[162:165], v[158:161], v[2:17]
	s_waitcnt lgkmcnt(1)
	v_mfma_f32_32x32x16_bf16 v[18:33], v[166:169], v[170:173], v[18:33]
	s_waitcnt lgkmcnt(0)
	v_mfma_f32_32x32x16_bf16 v[2:17], v[174:177], v[170:173], v[2:17]
	s_waitcnt vmcnt(12)
	ds_write_b128 v218, v[114:117] offset:18432
	ds_write_b128 v218, v[118:121] offset:27648
	ds_write_b128 v218, v[122:125] offset:55296
	ds_write_b128 v218, v[126:129] offset:64512
	global_load_dwordx4 v[114:117], v210, s[0:1] offset:384
	global_load_dwordx4 v[118:121], v210, s[2:3] offset:384
	global_load_dwordx4 v[122:125], v214, s[4:5] offset:384
	global_load_dwordx4 v[126:129], v214, s[6:7] offset:384
	s_waitcnt lgkmcnt(0)
	s_barrier
	ds_read_b128 v[130:133], v219 offset:18432
	ds_read_b128 v[134:137], v220 offset:55296
	ds_read_b128 v[138:141], v219 offset:23040
	ds_read_b128 v[142:145], v219 offset:18464
	ds_read_b128 v[146:149], v220 offset:55328
	ds_read_b128 v[150:153], v219 offset:23072
	ds_read_b128 v[154:157], v219 offset:18496
	ds_read_b128 v[158:161], v220 offset:55360
	ds_read_b128 v[162:165], v219 offset:23104
	ds_read_b128 v[166:169], v219 offset:18528
	ds_read_b128 v[170:173], v220 offset:55392
	ds_read_b128 v[174:177], v219 offset:23136
	s_waitcnt lgkmcnt(10)
	v_mfma_f32_32x32x16_bf16 v[18:33], v[130:133], v[134:137], v[18:33]
	s_waitcnt lgkmcnt(9)
	v_mfma_f32_32x32x16_bf16 v[2:17], v[138:141], v[134:137], v[2:17]
	s_waitcnt lgkmcnt(7)
	v_mfma_f32_32x32x16_bf16 v[18:33], v[142:145], v[146:149], v[18:33]
	s_waitcnt lgkmcnt(6)
	v_mfma_f32_32x32x16_bf16 v[2:17], v[150:153], v[146:149], v[2:17]
	s_waitcnt lgkmcnt(4)
	v_mfma_f32_32x32x16_bf16 v[18:33], v[154:157], v[158:161], v[18:33]
	s_waitcnt lgkmcnt(3)
	v_mfma_f32_32x32x16_bf16 v[2:17], v[162:165], v[158:161], v[2:17]
	s_waitcnt lgkmcnt(1)
	v_mfma_f32_32x32x16_bf16 v[18:33], v[166:169], v[170:173], v[18:33]
	s_waitcnt lgkmcnt(0)
	v_mfma_f32_32x32x16_bf16 v[2:17], v[174:177], v[170:173], v[2:17]
	s_waitcnt vmcnt(32)
	s_nop 15
	v_lshlrev_b32_e32 v226, 16, v194
	v_and_b32_e32 v227, 0xffff0000, v194
	v_pk_fma_f32 v[34:35], v[226:227], v[18:19], v[34:35]
	v_lshlrev_b32_e32 v228, 16, v195
	v_and_b32_e32 v229, 0xffff0000, v195
	v_pk_fma_f32 v[36:37], v[228:229], v[20:21], v[36:37]
	v_lshlrev_b32_e32 v234, 16, v196
	v_and_b32_e32 v235, 0xffff0000, v196
	v_pk_fma_f32 v[38:39], v[234:235], v[22:23], v[38:39]
	v_lshlrev_b32_e32 v236, 16, v197
	v_and_b32_e32 v237, 0xffff0000, v197
	v_pk_fma_f32 v[40:41], v[236:237], v[24:25], v[40:41]
	v_lshlrev_b32_e32 v226, 16, v198
	v_and_b32_e32 v227, 0xffff0000, v198
	v_pk_fma_f32 v[42:43], v[226:227], v[26:27], v[42:43]
	v_lshlrev_b32_e32 v228, 16, v199
	v_and_b32_e32 v229, 0xffff0000, v199
	v_pk_fma_f32 v[44:45], v[228:229], v[28:29], v[44:45]
	v_lshlrev_b32_e32 v234, 16, v200
	v_and_b32_e32 v235, 0xffff0000, v200
	v_pk_fma_f32 v[46:47], v[234:235], v[30:31], v[46:47]
	v_lshlrev_b32_e32 v236, 16, v201
	v_and_b32_e32 v237, 0xffff0000, v201
	v_pk_fma_f32 v[48:49], v[236:237], v[32:33], v[48:49]
	v_lshlrev_b32_e32 v226, 16, v202
	v_and_b32_e32 v227, 0xffff0000, v202
	v_pk_fma_f32 v[50:51], v[226:227], v[2:3], v[50:51]
	v_lshlrev_b32_e32 v228, 16, v203
	v_and_b32_e32 v229, 0xffff0000, v203
	v_pk_fma_f32 v[52:53], v[228:229], v[4:5], v[52:53]
	v_lshlrev_b32_e32 v234, 16, v204
	v_and_b32_e32 v235, 0xffff0000, v204
	v_pk_fma_f32 v[54:55], v[234:235], v[6:7], v[54:55]
	v_lshlrev_b32_e32 v236, 16, v205
	v_and_b32_e32 v237, 0xffff0000, v205
	v_pk_fma_f32 v[56:57], v[236:237], v[8:9], v[56:57]
	v_lshlrev_b32_e32 v226, 16, v206
	v_and_b32_e32 v227, 0xffff0000, v206
	v_pk_fma_f32 v[58:59], v[226:227], v[10:11], v[58:59]
	v_lshlrev_b32_e32 v228, 16, v207
	v_and_b32_e32 v229, 0xffff0000, v207
	v_pk_fma_f32 v[60:61], v[228:229], v[12:13], v[60:61]
	v_lshlrev_b32_e32 v234, 16, v208
	v_and_b32_e32 v235, 0xffff0000, v208
	v_pk_fma_f32 v[62:63], v[234:235], v[14:15], v[62:63]
	v_lshlrev_b32_e32 v236, 16, v209
	v_and_b32_e32 v237, 0xffff0000, v209
	v_pk_fma_f32 v[64:65], v[236:237], v[16:17], v[64:65]
	v_cvt_pk_bf16_f32 v178, v34, v35
	v_cvt_pk_bf16_f32 v179, v36, v37
	v_cvt_pk_bf16_f32 v180, v38, v39
	v_cvt_pk_bf16_f32 v181, v40, v41
	v_cvt_pk_bf16_f32 v182, v42, v43
	v_cvt_pk_bf16_f32 v183, v44, v45
	v_cvt_pk_bf16_f32 v184, v46, v47
	v_cvt_pk_bf16_f32 v185, v48, v49
	v_cvt_pk_bf16_f32 v186, v50, v51
	v_cvt_pk_bf16_f32 v187, v52, v53
	v_cvt_pk_bf16_f32 v188, v54, v55
	v_cvt_pk_bf16_f32 v189, v56, v57
	v_cvt_pk_bf16_f32 v190, v58, v59
	v_cvt_pk_bf16_f32 v191, v60, v61
	v_cvt_pk_bf16_f32 v192, v62, v63
	v_cvt_pk_bf16_f32 v193, v64, v65
	global_store_dwordx4 v222, v[178:181], s[12:13]
	global_store_dwordx4 v222, v[182:185], s[12:13] offset:16
	global_store_dwordx4 v222, v[186:189], s[12:13] offset:64
	global_store_dwordx4 v222, v[190:193], s[12:13] offset:80
	s_waitcnt vmcnt(16)
	ds_write_b128 v218, v[66:69]
	ds_write_b128 v218, v[70:73] offset:9216
	ds_write_b128 v218, v[74:77] offset:36864
	ds_write_b128 v218, v[78:81] offset:46080
	global_load_dwordx4 v[66:69], v210, s[0:1] offset:512
	global_load_dwordx4 v[70:73], v210, s[2:3] offset:512
	global_load_dwordx4 v[74:77], v214, s[4:5] offset:512
	global_load_dwordx4 v[78:81], v214, s[6:7] offset:512
	s_waitcnt lgkmcnt(0)
	s_barrier
	s_add_i32 s31, s31, s30
	s_mov_b32 s58, s60
	s_mov_b32 s59, s61
	s_cmpk_lt_i32 s31, 0x400
	s_cbranch_scc1 .Lmrg_task
